# attention unit boundary: merged prologue round trips, hoisted head-norm gain loads, permlane32_swap-widened dwordx4 output stores
# speedup vs baseline: 1.0021x; 1.0021x over previous
.LBB0_199:
	s_nop 0
	v_mov_b32_e32 v3, v172
	s_and_b32 s5, s21, 7
	v_readfirstlane_b32 s4, v3
	s_ashr_i32 s11, s4, 8
	s_ashr_i32 s8, s4, 6
	s_ashr_i32 s4, s21, 8
	s_sub_i32 s4, 7, s4
	s_and_b32 s6, s4, 1
	s_lshl_b32 s4, s4, 3
	s_or_b32 s7, s4, 15
	s_sub_i32 s7, s7, s5
	s_or_b32 s4, s4, s5
	s_cmp_eq_u32 s6, 0
	s_cselect_b32 s23, s4, s7
	s_bfe_u32 s16, s21, 0x20006
	s_lshl_b32 s5, s8, 5
	v_and_b32_e32 v2, 31, v3
	s_lshl_b32 s9, s23, 7
	s_lshl_b32 s4, s16, 13
	s_and_b32 s10, s5, 0x60
	s_add_i32 s22, s9, s4
	v_or_b32_e32 v0, s10, v2
	v_or_b32_e32 v0, s22, v0
	s_bfe_u32 s17, s21, 0x30003
	v_lshlrev_b64 v[6:7], 11, v[0:1]
	v_lshl_add_u64 v[6:7], s[92:93], 0, v[6:7]
	s_lshl_b32 s80, s17, 8
	s_lshl_b32 s6, s11, 6
	v_bfe_u32 v4, v3, 5, 1
	v_lshl_add_u64 v[6:7], v[6:7], 0, s[80:81]
	s_ashr_i32 s7, s6, 31
	v_lshl_add_u64 v[6:7], s[6:7], 1, v[6:7]
	v_lshlrev_b32_e32 v0, 4, v4
	v_lshl_add_u64 v[6:7], v[6:7], 0, v[0:1]
	global_load_dwordx4 v[128:131], v[6:7], off
	global_load_dwordx4 v[132:135], v[6:7], off offset:32
	global_load_dwordx4 v[136:139], v[6:7], off offset:64
	global_load_dwordx4 v[140:143], v[6:7], off offset:96
	s_lshl_b32 s18, s17, 7
	v_cmp_eq_u32_e32 vcc, s27, v3
	s_and_saveexec_b64 s[6:7], vcc
	v_mov_b32_e32 v0, s66
	ds_write_b32 v0, v173
	s_or_b64 exec, exec, s[6:7]
	s_lshr_b32 s5, s21, 6
	s_lshr_b32 s6, s21, 3
	s_and_b32 s5, s5, 3
	s_and_b32 s6, s6, 7
	v_and_b32_e32 v0, 63, v3
	s_lshl_b32 s6, s6, 21
	s_lshl_b32 s5, s5, 24
	s_or_b32 s19, s5, s6
	s_lshl_b32 s5, s8, 2
	v_lshrrev_b32_e32 v5, 4, v0
	v_or_b32_e32 v6, s5, v5
	v_bitop3_b32 v5, s5, v3, v5 bitop3:0x36
	s_mov_b32 s5, s81
	v_ashrrev_i32_e32 v7, 31, v6
	v_lshl_add_u64 v[6:7], v[6:7], 0, s[4:5]
	v_lshlrev_b64 v[6:7], 11, v[6:7]
	v_lshl_add_u64 v[6:7], s[86:87], 0, v[6:7]
	s_lshl_b32 s4, s18, 1
	v_lshrrev_b32_e32 v10, 3, v0
	v_lshl_add_u64 v[6:7], v[6:7], 0, s[4:5]
	s_lshl_b32 s5, s17, 21
	s_lshl_b32 s6, s16, 24
	v_lshl_or_b32 v0, s8, 3, v10
	s_lshl_b32 s24, s8, 10
	s_or_b32 s5, s6, s5
	v_lshrrev_b32_e32 v11, 1, v0
	v_lshlrev_b32_e32 v8, 6, v0
	v_lshlrev_b32_e32 v0, 4, v5
	s_add_u32 s6, s98, s5
	v_xor_b32_e32 v12, v11, v3
	v_and_b32_e32 v0, 0xf0, v0
	s_addc_u32 s7, s99, 0
	s_add_i32 s5, s24, 0
	v_ashrrev_i32_e32 v9, 31, v8
	v_lshl_add_u64 v[144:145], v[6:7], 0, v[0:1]
	v_lshlrev_b32_e32 v0, 4, v12
	s_mov_b32 m0, s5
	v_lshl_add_u64 v[6:7], v[8:9], 1, s[6:7]
	v_and_b32_e32 v0, 0x70, v0
	global_load_lds_dwordx4 v[144:145], off
	v_lshl_add_u64 v[8:9], v[144:145], 0, s[60:61]
	s_add_i32 m0, s5, 0x2000
	v_lshl_add_u64 v[6:7], v[6:7], 0, v[0:1]
	global_load_lds_dwordx4 v[8:9], off
	s_add_i32 m0, s5, 0x10000
	v_lshl_add_u64 v[8:9], v[6:7], 0, s[44:45]
	global_load_lds_dwordx4 v[6:7], off
	s_add_i32 m0, s5, 0x12000
	s_mov_b64 s[6:7], 0x20000
	global_load_lds_dwordx4 v[8:9], off
	v_lshl_add_u64 v[8:9], v[144:145], 0, s[6:7]
	s_add_i32 m0, s5, 0x4000
	s_mov_b64 s[6:7], 0x30000
	global_load_lds_dwordx4 v[8:9], off
	v_lshl_add_u64 v[8:9], v[144:145], 0, s[6:7]
	s_add_i32 m0, s5, 0x6000
	s_mov_b64 s[6:7], 0x4000
	global_load_lds_dwordx4 v[8:9], off
	v_lshl_add_u64 v[8:9], v[6:7], 0, s[6:7]
	s_add_i32 m0, s5, 0x14000
	s_mov_b64 s[6:7], 0x6000
	global_load_lds_dwordx4 v[8:9], off
	v_lshl_add_u64 v[6:7], v[6:7], 0, s[6:7]
	s_add_i32 m0, s5, 0x16000
	v_and_b32_e32 v5, 19, v3
	global_load_lds_dwordx4 v[6:7], off
	v_add_u32_e32 v246, s18, v172
	v_ashrrev_i32_e32 v247, 31, v246
	v_lshl_add_u64 v[246:247], v[246:247], 2, s[76:77]
	global_load_dword v244, v[246:247], off
	v_lshl_add_u32 v245, v172, 2, s66
	v_lshlrev_b32_e32 v6, 1, v3
	v_lshrrev_b32_e32 v7, 1, v3
	v_and_b32_e32 v6, 8, v6
	v_and_b32_e32 v8, 4, v7
	v_lshlrev_b32_e32 v0, 3, v4
	v_or3_b32 v5, v6, v5, v8
	v_lshl_or_b32 v6, s11, 3, v4
	v_bitop3_b32 v4, v4, v7, 7 bitop3:0x78
	v_lshlrev_b32_e32 v149, 4, v4
	v_lshlrev_b32_e32 v4, 6, v10
	v_lshl_or_b32 v4, s8, 9, v4
	v_bitop3_b32 v6, v5, v6, 15 bitop3:0x6c
	v_lshlrev_b32_e32 v156, 8, v5
	s_add_i32 s5, s23, -1
	s_add_i32 s25, s23, 1
	v_ashrrev_i32_e32 v5, 31, v4
	v_bitop3_b32 v3, v11, 7, v3 bitop3:0x48
	v_lshlrev_b64 v[4:5], 1, v[4:5]
	s_add_u32 s6, s76, s19
	v_lshl_or_b32 v4, v3, 4, v4
	s_addc_u32 s7, s77, 0
	v_lshl_add_u64 v[146:147], s[6:7], 0, v[4:5]
	s_add_i32 s6, s9, s10
	s_addk_i32 s6, 0xff89
	v_lshlrev_b32_e32 v157, 7, v2
	v_add_u32_e32 v2, s6, v2
	v_mov_b32_e32 v14, v1
	v_mov_b32_e32 v15, v1
	v_lshlrev_b32_e32 v148, 4, v6
	v_sub_u32_e32 v158, v2, v0
	v_mov_b32_e32 v0, v1
	v_mov_b32_e32 v2, v1
	v_mov_b32_e32 v3, v1
	v_mov_b32_e32 v4, v1
	v_mov_b32_e32 v5, v1
	v_mov_b32_e32 v6, v1
	v_mov_b32_e32 v7, v1
	v_mov_b32_e32 v8, v1
	v_mov_b32_e32 v9, v1
	v_mov_b32_e32 v10, v1
	v_mov_b32_e32 v11, v1
	v_mov_b32_e32 v12, v1
	v_mov_b32_e32 v13, v1
	v_mov_b64_e32 v[30:31], v[14:15]
	v_mov_b64_e32 v[46:47], v[14:15]
	v_mov_b64_e32 v[62:63], v[14:15]
	v_mov_b64_e32 v[78:79], v[14:15]
	v_mov_b64_e32 v[94:95], v[14:15]
	v_xor_b32_e32 v150, 32, v148
	v_xor_b32_e32 v151, 32, v149
	v_xor_b32_e32 v152, 64, v148
	v_xor_b32_e32 v153, 64, v149
	v_xor_b32_e32 v154, 0x60, v148
	v_xor_b32_e32 v155, 0x60, v149
	s_mov_b32 s26, 0
	v_mov_b32_e32 v159, 0
	s_mov_b64 s[6:7], 0
	s_movk_i32 s8, 0xc0
	v_mov_b64_e32 v[28:29], v[12:13]
	v_mov_b64_e32 v[26:27], v[10:11]
	v_mov_b64_e32 v[24:25], v[8:9]
	v_mov_b64_e32 v[22:23], v[6:7]
	v_mov_b64_e32 v[20:21], v[4:5]
	v_mov_b64_e32 v[18:19], v[2:3]
	v_mov_b64_e32 v[16:17], v[0:1]
	v_mov_b64_e32 v[44:45], v[12:13]
	v_mov_b64_e32 v[42:43], v[10:11]
	v_mov_b64_e32 v[40:41], v[8:9]
	v_mov_b64_e32 v[38:39], v[6:7]
	v_mov_b64_e32 v[36:37], v[4:5]
	v_mov_b64_e32 v[34:35], v[2:3]
	v_mov_b64_e32 v[32:33], v[0:1]
	v_mov_b64_e32 v[60:61], v[12:13]
	v_mov_b64_e32 v[58:59], v[10:11]
	v_mov_b64_e32 v[56:57], v[8:9]
	v_mov_b64_e32 v[54:55], v[6:7]
	v_mov_b64_e32 v[52:53], v[4:5]
	v_mov_b64_e32 v[50:51], v[2:3]
	v_mov_b64_e32 v[48:49], v[0:1]
	v_mov_b64_e32 v[76:77], v[12:13]
	v_mov_b64_e32 v[74:75], v[10:11]
	v_mov_b64_e32 v[72:73], v[8:9]
	v_mov_b64_e32 v[70:71], v[6:7]
	v_mov_b64_e32 v[68:69], v[4:5]
	v_mov_b64_e32 v[66:67], v[2:3]
	v_mov_b64_e32 v[64:65], v[0:1]
	v_mov_b64_e32 v[92:93], v[12:13]
	v_mov_b64_e32 v[90:91], v[10:11]
	v_mov_b64_e32 v[88:89], v[8:9]
	v_mov_b64_e32 v[86:87], v[6:7]
	v_mov_b64_e32 v[84:85], v[4:5]
	v_mov_b64_e32 v[82:83], v[2:3]
	v_mov_b64_e32 v[80:81], v[0:1]
	s_waitcnt vmcnt(0)
	v_cmp_gt_i32_e32 vcc, s27, v172
	s_and_saveexec_b64 s[16:17], vcc
	ds_write_b32 v245, v244 offset:4
	s_or_b64 exec, exec, s[16:17]
	s_branch .LBB0_205

.LBB0_223:
	s_cmp_gt_i32 s6, 3
	s_waitcnt lgkmcnt(0)
	s_barrier
	s_cbranch_scc1 .LBB0_198
	s_lshl_b32 s6, s5, 14
	s_waitcnt vmcnt(0)
	v_add3_u32 v2, v7, v6, s6
	ds_read2_b32 v[6:7], v2 offset1:32
	ds_read2_b32 v[8:9], v2 offset0:64 offset1:96
	s_waitcnt lgkmcnt(1)
	v_fma_f32 v81, v64, v0, -v6
	v_fma_f32 v64, v65, v0, -v7
	v_add_u32_e32 v7, 0x400, v2
	s_waitcnt lgkmcnt(0)
	v_fma_f32 v65, v66, v0, -v8
	v_fma_f32 v66, v67, v0, -v9
	ds_read2_b32 v[8:9], v7 offset1:32
	v_mul_f32_e32 v6, v64, v64
	v_fmac_f32_e32 v6, v81, v81
	v_fmac_f32_e32 v6, v65, v65
	v_fmac_f32_e32 v6, v66, v66
	s_waitcnt lgkmcnt(0)
	v_fma_f32 v67, v68, v0, -v8
	v_fma_f32 v68, v69, v0, -v9
	ds_read2_b32 v[8:9], v7 offset0:64 offset1:96
	v_add_u32_e32 v7, 0x800, v2
	v_fmac_f32_e32 v6, v67, v67
	v_fmac_f32_e32 v6, v68, v68
	s_waitcnt lgkmcnt(0)
	v_fma_f32 v69, v70, v0, -v8
	v_fma_f32 v70, v71, v0, -v9
	ds_read2_b32 v[8:9], v7 offset1:32
	v_fmac_f32_e32 v6, v69, v69
	v_fmac_f32_e32 v6, v70, v70
	s_waitcnt lgkmcnt(0)
	v_fma_f32 v72, v72, v0, -v8
	v_fma_f32 v71, v73, v0, -v9
	ds_read2_b32 v[8:9], v7 offset0:64 offset1:96
	v_add_u32_e32 v7, 0xc00, v2
	v_fmac_f32_e32 v6, v72, v72
	v_fmac_f32_e32 v6, v71, v71
	s_waitcnt lgkmcnt(0)
	v_fma_f32 v82, v74, v0, -v8
	v_fma_f32 v75, v75, v0, -v9
	ds_read2_b32 v[8:9], v7 offset1:32
	v_fmac_f32_e32 v6, v82, v82
	v_fmac_f32_e32 v6, v75, v75
	s_waitcnt lgkmcnt(0)
	v_fma_f32 v74, v76, v0, -v8
	v_fma_f32 v73, v77, v0, -v9
	ds_read2_b32 v[8:9], v7 offset0:64 offset1:96
	v_add_u32_e32 v7, 0x1000, v2
	v_fmac_f32_e32 v6, v74, v74
	v_fmac_f32_e32 v6, v73, v73
	s_waitcnt lgkmcnt(0)
	v_fma_f32 v78, v78, v0, -v8
	v_fma_f32 v77, v79, v0, -v9
	ds_read2_b32 v[8:9], v7 offset1:32
	v_fmac_f32_e32 v6, v78, v78
	v_fmac_f32_e32 v6, v77, v77
	s_waitcnt lgkmcnt(0)
	v_fma_f32 v76, v48, v0, -v8
	v_fma_f32 v48, v49, v0, -v9
	ds_read2_b32 v[8:9], v7 offset0:64 offset1:96
	v_add_u32_e32 v7, 0x1400, v2
	v_fmac_f32_e32 v6, v76, v76
	v_fmac_f32_e32 v6, v48, v48
	s_waitcnt lgkmcnt(0)
	v_fma_f32 v79, v50, v0, -v8
	v_fma_f32 v51, v51, v0, -v9
	ds_read2_b32 v[8:9], v7 offset1:32
	v_fmac_f32_e32 v6, v79, v79
	v_fmac_f32_e32 v6, v51, v51
	s_waitcnt lgkmcnt(0)
	v_fma_f32 v50, v52, v0, -v8
	v_fma_f32 v49, v53, v0, -v9
	ds_read2_b32 v[8:9], v7 offset0:64 offset1:96
	v_add_u32_e32 v7, 0x1800, v2
	v_fmac_f32_e32 v6, v50, v50
	v_fmac_f32_e32 v6, v49, v49
	s_waitcnt lgkmcnt(0)
	v_fma_f32 v83, v54, v0, -v8
	v_fma_f32 v54, v55, v0, -v9
	ds_read2_b32 v[8:9], v7 offset1:32
	v_fmac_f32_e32 v6, v83, v83
	v_fmac_f32_e32 v6, v54, v54
	s_waitcnt lgkmcnt(0)
	v_fma_f32 v53, v56, v0, -v8
	v_fma_f32 v52, v57, v0, -v9
	ds_read2_b32 v[8:9], v7 offset0:64 offset1:96
	v_add_u32_e32 v7, 0x1c00, v2
	v_fmac_f32_e32 v6, v53, v53
	v_fmac_f32_e32 v6, v52, v52
	s_waitcnt lgkmcnt(0)
	v_fma_f32 v58, v58, v0, -v8
	v_fma_f32 v57, v59, v0, -v9
	ds_read2_b32 v[8:9], v7 offset1:32
	v_fmac_f32_e32 v6, v58, v58
	v_fmac_f32_e32 v6, v57, v57
	s_waitcnt lgkmcnt(0)
	v_fma_f32 v56, v60, v0, -v8
	v_fma_f32 v55, v61, v0, -v9
	ds_read2_b32 v[8:9], v7 offset0:64 offset1:96
	v_add_u32_e32 v7, 0x2000, v2
	v_fmac_f32_e32 v6, v56, v56
	v_fmac_f32_e32 v6, v55, v55
	s_waitcnt lgkmcnt(0)
	v_fma_f32 v61, v62, v0, -v8
	v_fma_f32 v60, v63, v0, -v9
	ds_read2_b32 v[8:9], v7 offset1:32
	v_fmac_f32_e32 v6, v61, v61
	v_fmac_f32_e32 v6, v60, v60
	s_waitcnt lgkmcnt(0)
	v_fma_f32 v59, v32, v0, -v8
	v_fma_f32 v32, v33, v0, -v9
	ds_read2_b32 v[8:9], v7 offset0:64 offset1:96
	v_add_u32_e32 v7, 0x2400, v2
	v_fmac_f32_e32 v6, v59, v59
	v_fmac_f32_e32 v6, v32, v32
	s_waitcnt lgkmcnt(0)
	v_fma_f32 v63, v34, v0, -v8
	v_fma_f32 v62, v35, v0, -v9
	ds_read2_b32 v[8:9], v7 offset1:32
	v_fmac_f32_e32 v6, v63, v63
	v_fmac_f32_e32 v6, v62, v62
	s_waitcnt lgkmcnt(0)
	v_fma_f32 v36, v36, v0, -v8
	v_fma_f32 v34, v37, v0, -v9
	ds_read2_b32 v[8:9], v7 offset0:64 offset1:96
	v_add_u32_e32 v7, 0x2800, v2
	v_fmac_f32_e32 v6, v36, v36
	v_fmac_f32_e32 v6, v34, v34
	s_waitcnt lgkmcnt(0)
	v_fma_f32 v85, v38, v0, -v8
	v_fma_f32 v84, v39, v0, -v9
	ds_read2_b32 v[8:9], v7 offset1:32
	v_fmac_f32_e32 v6, v85, v85
	v_fmac_f32_e32 v6, v84, v84
	s_waitcnt lgkmcnt(0)
	v_fma_f32 v40, v40, v0, -v8
	v_fma_f32 v39, v41, v0, -v9
	ds_read2_b32 v[8:9], v7 offset0:64 offset1:96
	v_add_u32_e32 v7, 0x2c00, v2
	v_fmac_f32_e32 v6, v40, v40
	v_fmac_f32_e32 v6, v39, v39
	s_waitcnt lgkmcnt(0)
	v_fma_f32 v87, v42, v0, -v8
	v_fma_f32 v86, v43, v0, -v9
	ds_read2_b32 v[8:9], v7 offset1:32
	v_fmac_f32_e32 v6, v87, v87
	v_fmac_f32_e32 v6, v86, v86
	s_waitcnt lgkmcnt(0)
	v_fma_f32 v44, v44, v0, -v8
	v_fma_f32 v43, v45, v0, -v9
	ds_read2_b32 v[8:9], v7 offset0:64 offset1:96
	v_add_u32_e32 v7, 0x3000, v2
	v_fmac_f32_e32 v6, v44, v44
	v_fmac_f32_e32 v6, v43, v43
	s_waitcnt lgkmcnt(0)
	v_fma_f32 v42, v46, v0, -v8
	v_fma_f32 v41, v47, v0, -v9
	ds_read2_b32 v[8:9], v7 offset1:32
	v_fmac_f32_e32 v6, v42, v42
	v_fmac_f32_e32 v6, v41, v41
	s_waitcnt lgkmcnt(0)
	v_fma_f32 v38, v16, v0, -v8
	v_fma_f32 v37, v17, v0, -v9
	ds_read2_b32 v[8:9], v7 offset0:64 offset1:96
	v_add_u32_e32 v7, 0x3400, v2
	v_fmac_f32_e32 v6, v38, v38
	v_fmac_f32_e32 v6, v37, v37
	s_waitcnt lgkmcnt(0)
	v_fma_f32 v35, v18, v0, -v8
	v_fma_f32 v33, v19, v0, -v9
	ds_read2_b32 v[8:9], v7 offset1:32
	v_fmac_f32_e32 v6, v35, v35
	v_fmac_f32_e32 v6, v33, v33
	s_waitcnt lgkmcnt(0)
	v_fma_f32 v20, v20, v0, -v8
	v_fma_f32 v19, v21, v0, -v9
	ds_read2_b32 v[8:9], v7 offset0:64 offset1:96
	v_fmac_f32_e32 v6, v20, v20
	v_fmac_f32_e32 v6, v19, v19
	v_lshlrev_b32_e32 v21, 4, v80
	s_waitcnt lgkmcnt(0)
	v_pk_fma_f32 v[14:15], v[22:23], v[0:1], v[8:9] op_sel_hi:[1,0,1] neg_lo:[0,0,1] neg_hi:[0,0,1]
	s_nop 0
	v_pk_mul_f32 v[8:9], v[14:15], v[14:15]
	s_nop 0
	v_add_f32_e32 v6, v6, v8
	v_add_f32_e32 v8, v6, v9
	v_add_u32_e32 v9, 0x3800, v2
	ds_read2_b32 v[6:7], v9 offset1:32
	v_add_u32_e32 v2, 0x3c00, v2
	s_waitcnt lgkmcnt(0)
	v_pk_fma_f32 v[12:13], v[24:25], v[0:1], v[6:7] op_sel_hi:[1,0,1] neg_lo:[0,0,1] neg_hi:[0,0,1]
	s_nop 0
	v_pk_mul_f32 v[6:7], v[12:13], v[12:13]
	s_nop 0
	v_add_f32_e32 v6, v8, v6
	v_add_f32_e32 v8, v6, v7
	ds_read2_b32 v[6:7], v9 offset0:64 offset1:96
	s_waitcnt lgkmcnt(0)
	v_pk_fma_f32 v[10:11], v[26:27], v[0:1], v[6:7] op_sel_hi:[1,0,1] neg_lo:[0,0,1] neg_hi:[0,0,1]
	s_nop 0
	v_pk_mul_f32 v[6:7], v[10:11], v[10:11]
	s_nop 0
	v_add_f32_e32 v6, v8, v6
	v_add_f32_e32 v16, v6, v7
	ds_read2_b32 v[6:7], v2 offset1:32
	s_waitcnt lgkmcnt(0)
	v_pk_fma_f32 v[8:9], v[28:29], v[0:1], v[6:7] op_sel_hi:[1,0,1] neg_lo:[0,0,1] neg_hi:[0,0,1]
	s_nop 0
	v_pk_mul_f32 v[6:7], v[8:9], v[8:9]
	s_nop 0
	v_add_f32_e32 v6, v16, v6
	v_add_f32_e32 v18, v6, v7
	ds_read2_b32 v[6:7], v2 offset0:64 offset1:96
	s_waitcnt lgkmcnt(0)
	v_pk_fma_f32 v[6:7], v[30:31], v[0:1], v[6:7] op_sel_hi:[1,0,1] neg_lo:[0,0,1] neg_hi:[0,0,1]
	s_nop 0
	v_pk_mul_f32 v[16:17], v[6:7], v[6:7]
	s_nop 0
	v_add_f32_e32 v0, v18, v16
	v_add_f32_e32 v0, v0, v17
	ds_bpermute_b32 v2, v5, v0
	s_waitcnt lgkmcnt(0)
	v_add_f32_e32 v0, v0, v2
	v_fmamk_f32 v0, v0, 0x3c000000, v174
	v_cmp_gt_f32_e32 vcc, s90, v0
	v_mul_f32_e32 v2, 0x4b800000, v0
	s_nop 0
	v_cndmask_b32_e32 v0, v0, v2, vcc
	v_rsq_f32_e32 v0, v0
	s_nop 0
	v_mul_f32_e32 v2, 0x45800000, v0
	v_cndmask_b32_e32 v0, v0, v2, vcc
	v_mul_f32_e32 v18, v3, v0
	v_lshl_or_b32 v0, s5, 5, v4
	v_or_b32_e32 v0, s22, v0
	v_lshlrev_b64 v[2:3], 11, v[0:1]
	v_lshl_add_u64 v[2:3], s[84:85], 0, v[2:3]
	s_mov_b32 s5, s81
	v_lshl_add_u64 v[16:17], v[2:3], 0, s[4:5]
	global_load_dwordx4 v[2:5], v21, s[2:3]
	global_load_dwordx4 v[196:199], v21, s[2:3] offset:32
	global_load_dwordx4 v[200:203], v21, s[2:3] offset:64
	global_load_dwordx4 v[204:207], v21, s[2:3] offset:96
	global_load_dwordx4 v[208:211], v21, s[2:3] offset:128
	global_load_dwordx4 v[212:215], v21, s[2:3] offset:160
	global_load_dwordx4 v[216:219], v21, s[2:3] offset:192
	global_load_dwordx4 v[220:223], v21, s[2:3] offset:224
	global_load_dwordx4 v[224:227], v21, s[2:3] offset:256
	global_load_dwordx4 v[228:231], v21, s[2:3] offset:288
	global_load_dwordx4 v[232:235], v21, s[2:3] offset:320
	global_load_dwordx4 v[236:239], v21, s[2:3] offset:352
	global_load_dwordx4 v[244:247], v21, s[2:3] offset:384
	global_load_dwordx4 v[248:251], v21, s[2:3] offset:416
	global_load_dwordx4 v[252:255], v21, s[2:3] offset:448
	global_load_dwordx4 v[148:151], v21, s[2:3] offset:480
	v_mul_f32_e32 v0, v81, v18
	s_waitcnt vmcnt(0)
	v_mul_f32_e32 v0, v2, v0
	v_mul_f32_e32 v2, v64, v18
	v_mul_f32_e32 v2, v3, v2
	v_cvt_pk_bf16_f32 v152, v0, v2
	v_mul_f32_e32 v0, v65, v18
	v_mul_f32_e32 v0, v4, v0
	v_mul_f32_e32 v2, v66, v18
	v_mul_f32_e32 v2, v5, v2
	v_cvt_pk_bf16_f32 v153, v0, v2
	v_lshlrev_b32_e32 v0, 3, v80
	v_lshl_add_u64 v[2:3], v[16:17], 0, v[0:1]
	v_lshl_add_u64 v[160:161], v[2:3], 0, v[0:1]
	s_nop 0
	s_nop 0
	v_mul_f32_e32 v0, v67, v18
	v_mul_f32_e32 v4, v68, v18
	v_mul_f32_e32 v5, v70, v18
	s_nop 1
	v_mov_b32_e32 v22, v196
	v_mov_b32_e32 v23, v197
	v_mov_b32_e32 v24, v198
	v_mov_b32_e32 v25, v199
	s_nop 0
	v_mul_f32_e32 v0, v22, v0
	v_mul_f32_e32 v4, v23, v4
	v_cvt_pk_bf16_f32 v154, v0, v4
	v_mul_f32_e32 v0, v69, v18
	v_mul_f32_e32 v5, v25, v5
	v_mul_f32_e32 v0, v24, v0
	v_cvt_pk_bf16_f32 v155, v0, v5
	s_nop 1
	v_permlane32_swap_b32_e32 v152, v154
	v_permlane32_swap_b32_e32 v153, v155
	global_store_dwordx4 v[160:161], v[152:155], off offset:0
	s_nop 0
	v_mul_f32_e32 v0, v72, v18
	v_mul_f32_e32 v4, v71, v18
	v_mul_f32_e32 v5, v75, v18
	s_nop 1
	v_mov_b32_e32 v22, v200
	v_mov_b32_e32 v23, v201
	v_mov_b32_e32 v24, v202
	v_mov_b32_e32 v25, v203
	s_nop 0
	v_mul_f32_e32 v0, v22, v0
	v_mul_f32_e32 v4, v23, v4
	v_cvt_pk_bf16_f32 v156, v0, v4
	v_mul_f32_e32 v0, v82, v18
	v_mul_f32_e32 v5, v25, v5
	v_mul_f32_e32 v0, v24, v0
	v_cvt_pk_bf16_f32 v157, v0, v5
	s_nop 0
	s_nop 0
	v_mul_f32_e32 v0, v74, v18
	v_mul_f32_e32 v4, v73, v18
	v_mul_f32_e32 v5, v77, v18
	s_nop 1
	v_mov_b32_e32 v22, v204
	v_mov_b32_e32 v23, v205
	v_mov_b32_e32 v24, v206
	v_mov_b32_e32 v25, v207
	s_nop 0
	v_mul_f32_e32 v0, v0, v22
	v_mul_f32_e32 v4, v4, v23
	v_cvt_pk_bf16_f32 v158, v0, v4
	v_mul_f32_e32 v0, v78, v18
	v_mul_f32_e32 v5, v5, v25
	v_mul_f32_e32 v0, v0, v24
	v_cvt_pk_bf16_f32 v159, v0, v5
	s_nop 1
	v_permlane32_swap_b32_e32 v156, v158
	v_permlane32_swap_b32_e32 v157, v159
	global_store_dwordx4 v[160:161], v[156:159], off offset:32
	s_nop 0
	v_mul_f32_e32 v0, v76, v18
	v_mul_f32_e32 v4, v48, v18
	v_mul_f32_e32 v5, v51, v18
	s_nop 1
	v_mov_b32_e32 v22, v208
	v_mov_b32_e32 v23, v209
	v_mov_b32_e32 v24, v210
	v_mov_b32_e32 v25, v211
	s_nop 0
	v_mul_f32_e32 v0, v0, v22
	v_mul_f32_e32 v4, v4, v23
	v_cvt_pk_bf16_f32 v152, v0, v4
	v_mul_f32_e32 v0, v79, v18
	v_mul_f32_e32 v5, v5, v25
	v_mul_f32_e32 v0, v0, v24
	v_cvt_pk_bf16_f32 v153, v0, v5
	s_nop 0
	s_nop 0
	v_mul_f32_e32 v0, v50, v18
	v_mul_f32_e32 v4, v49, v18
	v_mul_f32_e32 v5, v54, v18
	s_nop 1
	v_mov_b32_e32 v22, v212
	v_mov_b32_e32 v23, v213
	v_mov_b32_e32 v24, v214
	v_mov_b32_e32 v25, v215
	s_nop 0
	v_mul_f32_e32 v0, v0, v22
	v_mul_f32_e32 v4, v4, v23
	v_cvt_pk_bf16_f32 v154, v0, v4
	v_mul_f32_e32 v0, v83, v18
	v_mul_f32_e32 v5, v5, v25
	v_mul_f32_e32 v0, v0, v24
	v_cvt_pk_bf16_f32 v155, v0, v5
	s_nop 1
	v_permlane32_swap_b32_e32 v152, v154
	v_permlane32_swap_b32_e32 v153, v155
	global_store_dwordx4 v[160:161], v[152:155], off offset:64
	s_nop 0
	v_mul_f32_e32 v0, v53, v18
	v_mul_f32_e32 v4, v52, v18
	v_mul_f32_e32 v5, v57, v18
	s_nop 1
	v_mov_b32_e32 v22, v216
	v_mov_b32_e32 v23, v217
	v_mov_b32_e32 v24, v218
	v_mov_b32_e32 v25, v219
	s_nop 0
	v_mul_f32_e32 v0, v0, v22
	v_mul_f32_e32 v4, v4, v23
	v_cvt_pk_bf16_f32 v156, v0, v4
	v_mul_f32_e32 v0, v58, v18
	v_mul_f32_e32 v5, v5, v25
	v_mul_f32_e32 v0, v0, v24
	v_cvt_pk_bf16_f32 v157, v0, v5
	s_nop 0
	s_nop 0
	v_mul_f32_e32 v0, v56, v18
	v_mul_f32_e32 v4, v55, v18
	v_mul_f32_e32 v5, v60, v18
	s_nop 1
	v_mov_b32_e32 v22, v220
	v_mov_b32_e32 v23, v221
	v_mov_b32_e32 v24, v222
	v_mov_b32_e32 v25, v223
	s_nop 0
	v_mul_f32_e32 v0, v0, v22
	v_mul_f32_e32 v4, v4, v23
	v_cvt_pk_bf16_f32 v158, v0, v4
	v_mul_f32_e32 v0, v61, v18
	v_mul_f32_e32 v5, v5, v25
	v_mul_f32_e32 v0, v0, v24
	v_cvt_pk_bf16_f32 v159, v0, v5
	s_nop 1
	v_permlane32_swap_b32_e32 v156, v158
	v_permlane32_swap_b32_e32 v157, v159
	global_store_dwordx4 v[160:161], v[156:159], off offset:96
	s_nop 0
	v_mul_f32_e32 v0, v59, v18
	v_mul_f32_e32 v4, v32, v18
	v_mul_f32_e32 v5, v62, v18
	s_nop 1
	v_mov_b32_e32 v22, v224
	v_mov_b32_e32 v23, v225
	v_mov_b32_e32 v24, v226
	v_mov_b32_e32 v25, v227
	s_nop 0
	v_mul_f32_e32 v0, v0, v22
	v_mul_f32_e32 v4, v4, v23
	v_cvt_pk_bf16_f32 v152, v0, v4
	v_mul_f32_e32 v0, v63, v18
	v_mul_f32_e32 v5, v5, v25
	v_mul_f32_e32 v0, v0, v24
	v_cvt_pk_bf16_f32 v153, v0, v5
	s_nop 0
	s_nop 0
	v_mul_f32_e32 v0, v36, v18
	v_mul_f32_e32 v4, v34, v18
	v_mul_f32_e32 v5, v84, v18
	s_nop 1
	v_mov_b32_e32 v22, v228
	v_mov_b32_e32 v23, v229
	v_mov_b32_e32 v24, v230
	v_mov_b32_e32 v25, v231
	s_nop 0
	v_mul_f32_e32 v0, v0, v22
	v_mul_f32_e32 v4, v4, v23
	v_cvt_pk_bf16_f32 v154, v0, v4
	v_mul_f32_e32 v0, v85, v18
	v_mul_f32_e32 v5, v5, v25
	v_mul_f32_e32 v0, v0, v24
	v_cvt_pk_bf16_f32 v155, v0, v5
	s_nop 1
	v_permlane32_swap_b32_e32 v152, v154
	v_permlane32_swap_b32_e32 v153, v155
	global_store_dwordx4 v[160:161], v[152:155], off offset:128
	s_nop 0
	v_mul_f32_e32 v0, v40, v18
	v_mul_f32_e32 v4, v39, v18
	v_mul_f32_e32 v5, v86, v18
	s_nop 1
	v_mov_b32_e32 v22, v232
	v_mov_b32_e32 v23, v233
	v_mov_b32_e32 v24, v234
	v_mov_b32_e32 v25, v235
	s_nop 0
	v_mul_f32_e32 v0, v0, v22
	v_mul_f32_e32 v4, v4, v23
	v_cvt_pk_bf16_f32 v156, v0, v4
	v_mul_f32_e32 v0, v87, v18
	v_mul_f32_e32 v5, v5, v25
	v_mul_f32_e32 v0, v0, v24
	v_cvt_pk_bf16_f32 v157, v0, v5
	s_nop 0
	s_nop 0
	v_mul_f32_e32 v0, v44, v18
	v_mul_f32_e32 v4, v43, v18
	v_mul_f32_e32 v5, v41, v18
	s_nop 1
	v_mov_b32_e32 v22, v236
	v_mov_b32_e32 v23, v237
	v_mov_b32_e32 v24, v238
	v_mov_b32_e32 v25, v239
	s_nop 0
	v_mul_f32_e32 v0, v0, v22
	v_mul_f32_e32 v4, v4, v23
	v_cvt_pk_bf16_f32 v158, v0, v4
	v_mul_f32_e32 v0, v42, v18
	v_mul_f32_e32 v5, v5, v25
	v_mul_f32_e32 v0, v0, v24
	v_cvt_pk_bf16_f32 v159, v0, v5
	s_nop 1
	v_permlane32_swap_b32_e32 v156, v158
	v_permlane32_swap_b32_e32 v157, v159
	global_store_dwordx4 v[160:161], v[156:159], off offset:160
	s_nop 0
	v_mul_f32_e32 v0, v38, v18
	v_mul_f32_e32 v4, v37, v18
	v_mul_f32_e32 v5, v33, v18
	s_nop 1
	v_mov_b32_e32 v22, v244
	v_mov_b32_e32 v23, v245
	v_mov_b32_e32 v24, v246
	v_mov_b32_e32 v25, v247
	s_nop 0
	v_mul_f32_e32 v0, v0, v22
	v_mul_f32_e32 v4, v4, v23
	v_cvt_pk_bf16_f32 v152, v0, v4
	v_mul_f32_e32 v0, v35, v18
	v_mul_f32_e32 v5, v5, v25
	v_mul_f32_e32 v0, v0, v24
	v_cvt_pk_bf16_f32 v153, v0, v5
	s_nop 0
	s_nop 0
	v_mul_f32_e32 v0, v20, v18
	v_mul_f32_e32 v4, v19, v18
	v_mul_f32_e32 v5, v15, v18
	s_nop 1
	v_mov_b32_e32 v22, v248
	v_mov_b32_e32 v23, v249
	v_mov_b32_e32 v24, v250
	v_mov_b32_e32 v25, v251
	s_nop 0
	v_mul_f32_e32 v0, v0, v22
	v_mul_f32_e32 v4, v4, v23
	v_cvt_pk_bf16_f32 v154, v0, v4
	v_mul_f32_e32 v0, v14, v18
	v_mul_f32_e32 v5, v5, v25
	v_mul_f32_e32 v0, v0, v24
	v_cvt_pk_bf16_f32 v155, v0, v5
	s_nop 1
	v_permlane32_swap_b32_e32 v152, v154
	v_permlane32_swap_b32_e32 v153, v155
	global_store_dwordx4 v[160:161], v[152:155], off offset:192
	s_nop 0
	v_mul_f32_e32 v0, v12, v18
	v_mul_f32_e32 v4, v13, v18
	v_mul_f32_e32 v5, v11, v18
	s_nop 1
	v_mov_b32_e32 v14, v252
	v_mov_b32_e32 v15, v253
	v_mov_b32_e32 v16, v254
	v_mov_b32_e32 v17, v255
	s_nop 0
	v_mul_f32_e32 v0, v0, v14
	v_mul_f32_e32 v4, v4, v15
	v_cvt_pk_bf16_f32 v156, v0, v4
	v_mul_f32_e32 v0, v10, v18
	v_mul_f32_e32 v5, v5, v17
	v_mul_f32_e32 v0, v0, v16
	v_cvt_pk_bf16_f32 v157, v0, v5
	s_nop 0
	s_nop 0
	v_mul_f32_e32 v0, v8, v18
	v_mul_f32_e32 v4, v9, v18
	v_mul_f32_e32 v5, v7, v18
	s_nop 1
	v_mov_b32_e32 v10, v148
	v_mov_b32_e32 v11, v149
	v_mov_b32_e32 v12, v150
	v_mov_b32_e32 v13, v151
	s_nop 0
	v_mul_f32_e32 v0, v0, v10
	v_mul_f32_e32 v4, v4, v11
	v_cvt_pk_bf16_f32 v158, v0, v4
	v_mul_f32_e32 v0, v6, v18
	v_mul_f32_e32 v5, v5, v13
	v_mul_f32_e32 v0, v0, v12
	v_cvt_pk_bf16_f32 v159, v0, v5
	s_nop 1
	v_permlane32_swap_b32_e32 v156, v158
	v_permlane32_swap_b32_e32 v157, v159
	global_store_dwordx4 v[160:161], v[156:159], off offset:224
	s_branch .LBB0_198
